# post-mix loops: next token rows / next transpose tile prefetched one step ahead, norm weights hoisted, batched LDS reads; attention S phase runs at s_setprio 1
# speedup vs baseline: 1.1033x; 1.0051x over previous
; #define MFMA32(a, b, c) __builtin_amdgcn_mfma_f32_32x32x16_bf16((a), (b), (c), 0, 0, 0)
; #define ATT_LOAD(KT)                                                                                    \
;   { _Pragma("unroll") for (int r = 0; r < 3; ++r) rk[r] = *(const u32x4*)(Kg + (size_t)((KT) * 64 + krow[r]) * 768 + kseg[r]); \
;     _Pragma("unroll") for (int r = 0; r < 2; ++r) rv[r] = *(const u32x4*)(Vg + (size_t)(vrow0 + 64 * r) * L + (KT) * 64 + vseg); }
; DI void attn_item(const Ctx& c, int item) {
;     ...
;     const bf16* ks_ = Ks + (kt & 1) * KSZ; const bf16* vs_ = Vs + (kt & 1) * VSZ;
;     f32x16 s[2];
; #pragma unroll
;     for (int kg = 0; kg < 2; ++kg)
; #pragma unroll
;       for (int i = 0; i < 16; ++i) s[kg][i] = 0.f;
; #pragma unroll
;     for (int ks = 0; ks < 12; ++ks)
; #pragma unroll
;       for (int kg = 0; kg < 2; ++kg) {
;         const bf16x8 a = *(const bf16x8*)(ks_ + (kg * 32 + r32) * 200 + ks * 16 + 8 * hh);
;         s[kg] = MFMA32(a, bq[ks], s[kg]);
;       }
;     ...
;     if (kt + 1 < ntile) ATT_STORE((kt + 1) & 1)
;     if (kt + 2 < ntile) ATT_LOAD(kt + 2)
.LBB0_547:
	s_and_b32 s0, s4, 1
	s_mul_i32 s1, s0, 0x6400
	v_mov_b32_e32 v0, v211
	v_add_u32_e32 v211, s1, v208
	s_setprio 1
	ds_read_b128 v[230:233], v211
	ds_read_b128 v[234:237], v211 offset:12800
	ds_read_b128 v[238:241], v211 offset:32
	ds_read_b128 v[242:245], v211 offset:12832
	s_waitcnt lgkmcnt(3)
	v_mfma_f32_32x32x16_bf16 v[82:97], v[230:233], v[98:101], 0
	ds_read_b128 v[230:233], v211 offset:64
	s_waitcnt lgkmcnt(3)
	v_mfma_f32_32x32x16_bf16 v[66:81], v[234:237], v[98:101], 0
	ds_read_b128 v[234:237], v211 offset:12864
	s_waitcnt lgkmcnt(3)
	v_mfma_f32_32x32x16_bf16 v[82:97], v[238:241], v[102:105], v[82:97]
	ds_read_b128 v[238:241], v211 offset:96
	s_waitcnt lgkmcnt(3)
	v_mfma_f32_32x32x16_bf16 v[66:81], v[242:245], v[102:105], v[66:81]
	ds_read_b128 v[242:245], v211 offset:12896
	s_waitcnt lgkmcnt(3)
	v_mfma_f32_32x32x16_bf16 v[82:97], v[230:233], v[106:109], v[82:97]
	ds_read_b128 v[230:233], v211 offset:128
	s_waitcnt lgkmcnt(3)
	v_mfma_f32_32x32x16_bf16 v[66:81], v[234:237], v[106:109], v[66:81]
	ds_read_b128 v[234:237], v211 offset:12928
	s_waitcnt lgkmcnt(3)
	v_mfma_f32_32x32x16_bf16 v[82:97], v[238:241], v[110:113], v[82:97]
	ds_read_b128 v[238:241], v211 offset:160
	s_waitcnt lgkmcnt(3)
	v_mfma_f32_32x32x16_bf16 v[66:81], v[242:245], v[110:113], v[66:81]
	ds_read_b128 v[242:245], v211 offset:12960
	s_add_i32 s100, s4, 1
	s_cmp_ge_u32 s100, s8
	s_cbranch_scc1 .Lattn_nostore
	s_bitcmp1_b32 s100, 0
	s_cselect_b32 s101, 0x6400, 0
	s_cselect_b32 vcc_hi, 0x4800, 0
	s_addk_i32 s101, 0x50
	v_lshlrev_b32_e32 v212, 1, v168
	v_add3_u32 v212, s101, v169, v212
	s_waitcnt vmcnt(4)
	ds_write_b128 v212, v[146:149]
	v_lshlrev_b32_e32 v212, 1, v170
	v_add3_u32 v212, s101, v171, v212
	s_waitcnt vmcnt(3)
	ds_write_b128 v212, v[150:153]
	v_lshlrev_b32_e32 v212, 1, v172
	v_add3_u32 v212, s101, v173, v212
	s_waitcnt vmcnt(2)
	ds_write_b128 v212, v[154:157]
	v_add_u32_e32 v212, vcc_hi, v206
	v_add_u32_e32 v213, 0xc800, v212
	v_add_u32_e32 v212, 0xe800, v212
	s_waitcnt vmcnt(1)
	ds_write2_b64 v213, v[158:159], v[160:161] offset1:2
	s_waitcnt vmcnt(0)
	ds_write2_b64 v212, v[162:163], v[164:165] offset0:128 offset1:130

; #define MFMA32(a, b, c) __builtin_amdgcn_mfma_f32_32x32x16_bf16((a), (b), (c), 0, 0, 0)
; DI void attn_item(const Ctx& c, int item) {
;     ...
; #pragma unroll
;     for (int ks = 0; ks < 12; ++ks)
; #pragma unroll
;       for (int kg = 0; kg < 2; ++kg) {
;         const bf16x8 a = *(const bf16x8*)(ks_ + (kg * 32 + r32) * 200 + ks * 16 + 8 * hh);
;         s[kg] = MFMA32(a, bq[ks], s[kg]);
;       }
;     float mx = s[0][0];
; #pragma unroll
;     for (int kg = 0; kg < 2; ++kg)
; #pragma unroll
;       for (int i = 0; i < 16; ++i) mx = fmaxf(mx, s[kg][i]);
;     mx = fmaxf(mx, __shfl_xor(mx, 32));
;     const float mn = fmaxf(m_, mx * sc);
;     const float alpha = __builtin_amdgcn_exp2f(m_ - mn);
;     m_ = mn;
;     float ps = 0.f;
; #pragma unroll
;     for (int kg = 0; kg < 2; ++kg)
; #pragma unroll
;       for (int i = 0; i < 16; ++i) { s[kg][i] = __builtin_amdgcn_exp2f(s[kg][i] * sc - mn); ps += s[kg][i]; }
;     l_ = l_ * alpha + ps;
;     if (__builtin_amdgcn_ballot_w64(alpha != 1.0f) != 0ull) {
; #pragma unroll
;       for (int dt = 0; dt < 4; ++dt)
; #pragma unroll
;         for (int i = 0; i < 16; ++i) oacc[dt][i] *= alpha;
;     }
.Lattn_noload:
	s_waitcnt lgkmcnt(3)
	v_mfma_f32_32x32x16_bf16 v[82:97], v[230:233], v[114:117], v[82:97]
	ds_read_b128 v[230:233], v211 offset:192
	s_waitcnt lgkmcnt(3)
	v_mfma_f32_32x32x16_bf16 v[66:81], v[234:237], v[114:117], v[66:81]
	ds_read_b128 v[234:237], v211 offset:12992
	s_waitcnt lgkmcnt(3)
	v_mfma_f32_32x32x16_bf16 v[82:97], v[238:241], v[118:121], v[82:97]
	ds_read_b128 v[238:241], v211 offset:224
	s_waitcnt lgkmcnt(3)
	v_mfma_f32_32x32x16_bf16 v[66:81], v[242:245], v[118:121], v[66:81]
	ds_read_b128 v[242:245], v211 offset:13024
	s_waitcnt lgkmcnt(3)
	v_mfma_f32_32x32x16_bf16 v[82:97], v[230:233], v[122:125], v[82:97]
	ds_read_b128 v[230:233], v211 offset:256
	s_waitcnt lgkmcnt(3)
	v_mfma_f32_32x32x16_bf16 v[66:81], v[234:237], v[122:125], v[66:81]
	ds_read_b128 v[234:237], v211 offset:13056
	s_waitcnt lgkmcnt(3)
	v_mfma_f32_32x32x16_bf16 v[82:97], v[238:241], v[126:129], v[82:97]
	ds_read_b128 v[238:241], v211 offset:288
	s_waitcnt lgkmcnt(3)
	v_mfma_f32_32x32x16_bf16 v[66:81], v[242:245], v[126:129], v[66:81]
	ds_read_b128 v[242:245], v211 offset:13088
	s_waitcnt lgkmcnt(3)
	v_mfma_f32_32x32x16_bf16 v[82:97], v[230:233], v[130:133], v[82:97]
	ds_read_b128 v[230:233], v211 offset:320
	s_waitcnt lgkmcnt(3)
	v_mfma_f32_32x32x16_bf16 v[66:81], v[234:237], v[130:133], v[66:81]
	ds_read_b128 v[234:237], v211 offset:13120
	s_waitcnt lgkmcnt(3)
	v_mfma_f32_32x32x16_bf16 v[82:97], v[238:241], v[134:137], v[82:97]
	ds_read_b128 v[238:241], v211 offset:352
	s_waitcnt lgkmcnt(3)
	v_mfma_f32_32x32x16_bf16 v[66:81], v[242:245], v[134:137], v[66:81]
	ds_read_b128 v[242:245], v211 offset:13152
	s_waitcnt lgkmcnt(3)
	v_mfma_f32_32x32x16_bf16 v[82:97], v[230:233], v[138:141], v[82:97]
	s_waitcnt lgkmcnt(2)
	v_mfma_f32_32x32x16_bf16 v[66:81], v[234:237], v[138:141], v[66:81]
	s_waitcnt lgkmcnt(1)
	v_mfma_f32_32x32x16_bf16 v[82:97], v[238:241], v[142:145], v[82:97]
	s_waitcnt lgkmcnt(0)
	v_mfma_f32_32x32x16_bf16 v[66:81], v[242:245], v[142:145], v[66:81]
	s_setprio 0
	s_mulk_i32 s0, 0x4800
	v_add_u32_e32 v224, s0, v209
	ds_read_b128 v[230:233], v224 offset:51200
	ds_read_b128 v[234:237], v224 offset:55808
	ds_read_b128 v[238:241], v224 offset:60416
	ds_read_b128 v[242:245], v224 offset:65024
	ds_read_b128 v[246:249], v224 offset:51232
	s_nop 2
	v_max_f32_e32 v211, v83, v83
	v_max_f32_e32 v212, v82, v82
	v_max_f32_e32 v211, v212, v211
	v_max3_f32 v211, v211, v84, v85
	v_max3_f32 v211, v211, v86, v87
	v_max3_f32 v211, v211, v88, v89
	v_max3_f32 v211, v211, v90, v91
	v_max3_f32 v211, v211, v92, v93
	v_max3_f32 v211, v211, v94, v95
	v_max3_f32 v211, v211, v96, v97
	v_max3_f32 v211, v211, v66, v67
	v_max3_f32 v211, v211, v68, v69
	v_max3_f32 v211, v211, v70, v71
	v_max3_f32 v211, v211, v72, v73
	v_max3_f32 v211, v211, v74, v75
	v_max3_f32 v211, v211, v76, v77
	v_max3_f32 v211, v211, v78, v79
	v_max3_f32 v211, v211, v80, v81
	ds_bpermute_b32 v212, v207, v211
	s_waitcnt lgkmcnt(0)
	v_max_f32_e32 v212, v212, v212
	v_max_f32_e32 v211, v211, v212
	v_mul_f32_e32 v211, 0x3dd53b94, v211
	v_max_f32_e32 v212, v0, v0
	v_max_f32_e32 v211, v212, v211
	v_sub_f32_e32 v0, v0, v211
	v_exp_f32_e32 v0, v0
	s_nop 0
	v_cmp_neq_f32_e32 vcc, 1.0, v0
	s_cbranch_vccz .LBB0_549
	v_pk_mul_f32 v[64:65], v[64:65], v[0:1] op_sel_hi:[1,0]
	v_pk_mul_f32 v[62:63], v[62:63], v[0:1] op_sel_hi:[1,0]
	v_pk_mul_f32 v[60:61], v[60:61], v[0:1] op_sel_hi:[1,0]
	v_pk_mul_f32 v[58:59], v[58:59], v[0:1] op_sel_hi:[1,0]
	v_pk_mul_f32 v[56:57], v[56:57], v[0:1] op_sel_hi:[1,0]
	v_pk_mul_f32 v[54:55], v[54:55], v[0:1] op_sel_hi:[1,0]
	v_pk_mul_f32 v[52:53], v[52:53], v[0:1] op_sel_hi:[1,0]
	v_pk_mul_f32 v[50:51], v[50:51], v[0:1] op_sel_hi:[1,0]
	v_pk_mul_f32 v[48:49], v[48:49], v[0:1] op_sel_hi:[1,0]
	v_pk_mul_f32 v[46:47], v[46:47], v[0:1] op_sel_hi:[1,0]
	v_pk_mul_f32 v[44:45], v[44:45], v[0:1] op_sel_hi:[1,0]
	v_pk_mul_f32 v[42:43], v[42:43], v[0:1] op_sel_hi:[1,0]
	v_pk_mul_f32 v[40:41], v[40:41], v[0:1] op_sel_hi:[1,0]
	v_pk_mul_f32 v[38:39], v[38:39], v[0:1] op_sel_hi:[1,0]
	v_pk_mul_f32 v[36:37], v[36:37], v[0:1] op_sel_hi:[1,0]
	v_pk_mul_f32 v[34:35], v[34:35], v[0:1] op_sel_hi:[1,0]
	v_pk_mul_f32 v[32:33], v[32:33], v[0:1] op_sel_hi:[1,0]
	v_pk_mul_f32 v[30:31], v[30:31], v[0:1] op_sel_hi:[1,0]
	v_pk_mul_f32 v[28:29], v[28:29], v[0:1] op_sel_hi:[1,0]
	v_pk_mul_f32 v[26:27], v[26:27], v[0:1] op_sel_hi:[1,0]
	v_pk_mul_f32 v[24:25], v[24:25], v[0:1] op_sel_hi:[1,0]
	v_pk_mul_f32 v[22:23], v[22:23], v[0:1] op_sel_hi:[1,0]
	v_pk_mul_f32 v[20:21], v[20:21], v[0:1] op_sel_hi:[1,0]
	v_pk_mul_f32 v[18:19], v[18:19], v[0:1] op_sel_hi:[1,0]
	v_pk_mul_f32 v[16:17], v[16:17], v[0:1] op_sel_hi:[1,0]
	v_pk_mul_f32 v[14:15], v[14:15], v[0:1] op_sel_hi:[1,0]
	v_pk_mul_f32 v[12:13], v[12:13], v[0:1] op_sel_hi:[1,0]
	v_pk_mul_f32 v[10:11], v[10:11], v[0:1] op_sel_hi:[1,0]
	v_pk_mul_f32 v[8:9], v[8:9], v[0:1] op_sel_hi:[1,0]
	v_pk_mul_f32 v[6:7], v[6:7], v[0:1] op_sel_hi:[1,0]
	v_pk_mul_f32 v[4:5], v[4:5], v[0:1] op_sel_hi:[1,0]
	v_pk_mul_f32 v[2:3], v[2:3], v[0:1] op_sel_hi:[1,0]

; DI float siluf_(float x) { return x / (1.f + __expf(-x)); }
; DI void post_mix_rows(const Ctx& c, int m0) {
;     ...
;   for (int tk = wave; tk < 128; tk += 8) {
;     const int tok = m0 + tk;
;     float a[8], b[8], z[8], v[8];
;     unpack8(*(const uint4*)(OFp + (size_t)tok * 512 + lane * 8), a);
;     unpack8(*(const uint4*)(OBp + (size_t)tok * 512 + lane * 8), b);
;     unpack8(*(const uint4*)(Z + (size_t)tok * 512 + lane * 8), z);
;     float ss = 0.f;
; #pragma unroll
;     for (int e = 0; e < 8; ++e) { a[e] += b[e]; ss += a[e] * a[e]; }
;     ss += __shfl_xor(ss, 1); ss += __shfl_xor(ss, 2); ss += __shfl_xor(ss, 4); ss += __shfl_xor(ss, 8);
;     const float rs = rsqrtf(ss * (1.0f / 128.0f) + EPS);
; #pragma unroll
;     for (int e = 0; e < 8; ++e) v[e] = a[e] * rs * on[(lane & 15) * 8 + e] * siluf_(z[e]);
;     *(uint4*)(Og + (size_t)tok * 512 + lane * 8) = pack8(v);
.LBB0_791:
	v_mov_b32_e32 v12, v186
	s_movk_i32 s0, 0x80
	v_ashrrev_i32_e32 v4, 6, v12
	v_cmp_gt_i32_e32 vcc, s0, v4
	v_lshlrev_b32_e32 v13, 3, v12
	s_and_saveexec_b64 s[0:1], vcc
	s_mov_b32 s12, 0x800000
	s_mov_b64 s[14:15], 0x2000
	s_cbranch_execz .LBB0_794
	v_and_b32_e32 v2, 64, v189
	v_xor_b32_e32 v0, 1, v189
	v_add_u32_e32 v2, 64, v2
	v_cmp_lt_i32_e32 vcc, v0, v2
	v_readlane_b32 s10, v226, 35
	v_readlane_b32 s11, v226, 36
	v_cndmask_b32_e32 v0, v189, v0, vcc
	v_lshlrev_b32_e32 v14, 2, v0
	v_xor_b32_e32 v0, 2, v189
	v_cmp_lt_i32_e32 vcc, v0, v2
	v_and_b32_e32 v6, 63, v12
	s_mov_b64 s[18:19], 0
	v_cndmask_b32_e32 v0, v189, v0, vcc
	v_lshlrev_b32_e32 v15, 2, v0
	v_xor_b32_e32 v0, 4, v189
	v_cmp_lt_i32_e32 vcc, v0, v2
	s_nop 1
	v_cndmask_b32_e32 v0, v189, v0, vcc
	v_lshlrev_b32_e32 v16, 2, v0
	v_xor_b32_e32 v0, 8, v189
	v_cmp_lt_i32_e32 vcc, v0, v2
	s_nop 1
	v_cndmask_b32_e32 v0, v189, v0, vcc
	v_lshlrev_b32_e32 v17, 2, v0
	v_and_b32_e32 v0, 0x78, v13
	v_lshlrev_b32_e32 v0, 2, v0
	v_lshl_add_u64 v[2:3], s[10:11], 0, v[0:1]
	v_add_u32_e32 v0, -8, v4
	v_add_u32_e32 v4, s16, v4
	v_ashrrev_i32_e32 v5, 31, v4
	v_lshlrev_b64 v[4:5], 10, v[4:5]
	v_readlane_b32 s10, v228, 34
	v_lshl_or_b32 v4, v6, 4, v4
	v_readlane_b32 s11, v228, 35
	s_nop 1
	v_lshl_add_u64 v[4:5], s[10:11], 0, v[4:5]
	global_load_dwordx4 v[230:233], v[2:3], off offset:16
	global_load_dwordx4 v[234:237], v[2:3], off
	s_mov_b32 s10, 0xd5800000
	v_add_co_u32_e32 v254, vcc, s10, v4
	s_mov_b32 s10, 0xd3800000
	v_addc_co_u32_e32 v255, vcc, -1, v5, vcc
	global_load_dwordx4 v[242:245], v[4:5], off
	global_load_dwordx4 v[246:249], v[254:255], off
	v_add_co_u32_e32 v254, vcc, s10, v4
	s_nop 0
	v_addc_co_u32_e32 v255, vcc, -1, v5, vcc
	global_load_dwordx4 v[250:253], v[254:255], off
.LBB0_793:
	v_add_u32_e32 v0, 8, v0
	s_waitcnt vmcnt(0)
	v_mov_b32_e32 v8, v242
	v_mov_b32_e32 v9, v243
	v_mov_b32_e32 v10, v244
	v_mov_b32_e32 v11, v245
	v_mov_b32_e32 v18, v246
	v_mov_b32_e32 v19, v247
	v_mov_b32_e32 v20, v248
	v_mov_b32_e32 v21, v249
	v_mov_b32_e32 v238, v250
	v_mov_b32_e32 v239, v251
	v_mov_b32_e32 v240, v252
	v_mov_b32_e32 v241, v253
	v_readfirstlane_b32 s10, v0
	s_cmp_gt_i32 s10, 0x77
	s_cbranch_scc1 .Lpm_nopf
	v_lshl_add_u64 v[254:255], v[4:5], 0, s[14:15]
	s_mov_b32 s10, 0xd5800000
	global_load_dwordx4 v[242:245], v[254:255], off
	v_add_co_u32_e32 v6, vcc, s10, v254
	s_mov_b32 s10, 0xd3800000
	v_addc_co_u32_e32 v7, vcc, -1, v255, vcc
	global_load_dwordx4 v[246:249], v[6:7], off
	v_add_co_u32_e32 v6, vcc, s10, v254
	s_nop 0
	v_addc_co_u32_e32 v7, vcc, -1, v255, vcc
	global_load_dwordx4 v[250:253], v[6:7], off
.Lpm_nopf:
	v_lshlrev_b32_e32 v28, 16, v10
	v_and_b32_e32 v29, 0xffff0000, v10
	v_lshlrev_b32_e32 v6, 16, v8
	v_and_b32_e32 v7, 0xffff0000, v8
	v_lshlrev_b32_e32 v26, 16, v9
	v_and_b32_e32 v27, 0xffff0000, v9
	v_lshlrev_b32_e32 v8, 16, v11
	v_and_b32_e32 v9, 0xffff0000, v11
	v_lshlrev_b32_e32 v10, 16, v18
	v_and_b32_e32 v11, 0xffff0000, v18
	v_lshlrev_b32_e32 v30, 16, v19
	v_and_b32_e32 v31, 0xffff0000, v19
	v_lshlrev_b32_e32 v32, 16, v20
	v_and_b32_e32 v33, 0xffff0000, v20
	v_lshlrev_b32_e32 v22, 16, v21
	v_and_b32_e32 v23, 0xffff0000, v21
	v_pk_add_f32 v[8:9], v[8:9], v[22:23]
	v_pk_add_f32 v[6:7], v[6:7], v[10:11]
	v_pk_add_f32 v[26:27], v[26:27], v[30:31]
	v_pk_mul_f32 v[10:11], v[6:7], v[6:7]
	v_pk_mul_f32 v[30:31], v[26:27], v[26:27]
	v_add_f32_e32 v10, v10, v11
	v_pk_add_f32 v[28:29], v[28:29], v[32:33]
	v_add_f32_e32 v10, v10, v30
	v_pk_mul_f32 v[32:33], v[28:29], v[28:29]
	v_add_f32_e32 v10, v31, v10
	v_add_f32_e32 v10, v32, v10
	v_pk_mul_f32 v[34:35], v[8:9], v[8:9]
	v_add_f32_e32 v10, v33, v10
	v_add_f32_e32 v10, v34, v10
	v_add_f32_e32 v10, v35, v10
	ds_bpermute_b32 v11, v14, v10
	s_waitcnt lgkmcnt(0)
	v_add_f32_e32 v10, v10, v11
	ds_bpermute_b32 v11, v15, v10
	s_waitcnt lgkmcnt(0)
	v_add_f32_e32 v10, v10, v11
	ds_bpermute_b32 v11, v16, v10
	s_waitcnt lgkmcnt(0)
	v_add_f32_e32 v10, v10, v11
	ds_bpermute_b32 v11, v17, v10
	s_waitcnt lgkmcnt(0)
	v_add_f32_e32 v10, v10, v11
	v_fmamk_f32 v10, v10, 0x3c000000, v187
	v_mul_f32_e32 v11, 0x4b800000, v10
	v_lshlrev_b32_e32 v38, 16, v241
	v_and_b32_e32 v39, 0xffff0000, v241
	v_lshlrev_b32_e32 v44, 16, v238
	v_and_b32_e32 v45, 0xffff0000, v238
	v_mul_f32_e32 v18, 0xbfb8aa3b, v38
	v_mul_f32_e32 v37, 0xbfb8aa3b, v39
	v_exp_f32_e32 v36, v18
	v_exp_f32_e32 v37, v37
	v_lshlrev_b32_e32 v40, 16, v240
	v_and_b32_e32 v41, 0xffff0000, v240
	v_lshlrev_b32_e32 v42, 16, v239
	v_pk_add_f32 v[36:37], v[36:37], 1.0 op_sel_hi:[1,0]
	v_and_b32_e32 v43, 0xffff0000, v239
	v_min_f32_e32 v37, 0x7f7fffff, v37
	v_rcp_f32_e32 v254, v37
	s_nop 0
	v_fma_f32 v255, -v37, v254, 1.0
	v_fma_f32 v254, v255, v254, v254
	v_mul_f32_e32 v37, v39, v254
	v_min_f32_e32 v36, 0x7f7fffff, v36
	v_rcp_f32_e32 v254, v36
	s_nop 0
	v_fma_f32 v255, -v36, v254, 1.0
	v_fma_f32 v254, v255, v254, v254
	v_mul_f32_e32 v36, v38, v254
	v_mul_f32_e32 v38, 0xbfb8aa3b, v40
	v_mul_f32_e32 v39, 0xbfb8aa3b, v41
	v_exp_f32_e32 v38, v38
	v_exp_f32_e32 v39, v39
	s_nop 0
	v_pk_add_f32 v[38:39], v[38:39], 1.0 op_sel_hi:[1,0]
	s_nop 0
	v_min_f32_e32 v39, 0x7f7fffff, v39
	v_rcp_f32_e32 v254, v39
	s_nop 0
	v_fma_f32 v255, -v39, v254, 1.0
	v_fma_f32 v254, v255, v254, v254
	v_mul_f32_e32 v39, v41, v254
	v_min_f32_e32 v38, 0x7f7fffff, v38
	v_rcp_f32_e32 v254, v38
	s_nop 0
	v_fma_f32 v255, -v38, v254, 1.0
	v_fma_f32 v254, v255, v254, v254
	v_mul_f32_e32 v38, v40, v254
	v_mul_f32_e32 v40, 0xbfb8aa3b, v42
	v_mul_f32_e32 v41, 0xbfb8aa3b, v43
	v_exp_f32_e32 v40, v40
	v_exp_f32_e32 v41, v41
	s_nop 0
	v_pk_add_f32 v[40:41], v[40:41], 1.0 op_sel_hi:[1,0]
	s_nop 0
	v_min_f32_e32 v41, 0x7f7fffff, v41
; DI float siluf_(float x) { return x / (1.f + __expf(-x)); }
; DI void post_mix_rows(const Ctx& c, int m0) {
;     ...
;     const float rs = rsqrtf(ss * (1.0f / 128.0f) + EPS);
; #pragma unroll
;     for (int e = 0; e < 8; ++e) v[e] = a[e] * rs * on[(lane & 15) * 8 + e] * siluf_(z[e]);
;     *(uint4*)(Og + (size_t)tok * 512 + lane * 8) = pack8(v);
;   }
;   bf16* tile = (bf16*)c.smem;
;   const bf16* ZO = (const bf16*)(c.ws + OFF_ZOUT);
;   bf16* Oh = (bf16*)(c.ws + OFF_OHY);
;   const int L = c.L;
;   __syncthreads();
;   for (int it = 0; it < 16; ++it) {
;     const int t0 = m0 + (it & 1) * 64, c0 = (it >> 1) * 64, seq = t0 >> c.logL, n0 = t0 & (L - 1);
;     {
;       const int ch = tid >> 3, ts = (tid & 7) * 8;
;       *(uint4*)(tile + ch * 72 + ts) = *(const uint4*)(ZO + ((size_t)(seq * 512 + c0 + ch)) * L + n0 + ts);
;     }
;     __syncthreads();
;     {
;       const int tr = tid >> 3, cs = (tid & 7) * 8;
;       unsigned short v[8];
; #pragma unroll
;       for (int e = 0; e < 8; ++e) v[e] = tile[(cs + e) * 72 + tr];
;       uint4 o; o.x = v[0] | ((unsigned)v[1] << 16); o.y = v[2] | ((unsigned)v[3] << 16); o.z = v[4] | ((unsigned)v[5] << 16); o.w = v[6] | ((unsigned)v[7] << 16);
;       *(uint4*)(Oh + (size_t)(t0 + tr) * 512 + c0 + cs) = o;
;     }
;     __syncthreads();
;   }
	v_rcp_f32_e32 v254, v41
	s_nop 0
	v_fma_f32 v255, -v41, v254, 1.0
	v_fma_f32 v254, v255, v254, v254
	v_mul_f32_e32 v41, v43, v254
	v_min_f32_e32 v40, 0x7f7fffff, v40
	v_rcp_f32_e32 v254, v40
	s_nop 0
	v_fma_f32 v255, -v40, v254, 1.0
	v_fma_f32 v254, v255, v254, v254
	v_mul_f32_e32 v40, v42, v254
	v_mul_f32_e32 v42, 0xbfb8aa3b, v44
	v_mul_f32_e32 v43, 0xbfb8aa3b, v45
	v_exp_f32_e32 v42, v42
	v_exp_f32_e32 v43, v43
	s_nop 0
	v_pk_add_f32 v[42:43], v[42:43], 1.0 op_sel_hi:[1,0]
	s_nop 0
	v_min_f32_e32 v43, 0x7f7fffff, v43
	v_rcp_f32_e32 v254, v43
	s_nop 0
	v_fma_f32 v255, -v43, v254, 1.0
	v_fma_f32 v254, v255, v254, v254
	v_mul_f32_e32 v43, v45, v254
	s_movk_i32 s10, 0x77
	v_cmp_gt_f32_e32 vcc, s12, v10
	v_min_f32_e32 v42, 0x7f7fffff, v42
	v_rcp_f32_e32 v254, v42
	s_nop 0
	v_fma_f32 v255, -v42, v254, 1.0
	v_fma_f32 v254, v255, v254, v254
	v_mul_f32_e32 v42, v44, v254
	s_nop 0
	v_cndmask_b32_e32 v10, v10, v11, vcc
	v_rsq_f32_e32 v10, v10
	s_nop 0
	v_mul_f32_e32 v11, 0x45800000, v10
	v_cndmask_b32_e32 v10, v10, v11, vcc
	v_pk_mul_f32 v[6:7], v[6:7], v[10:11] op_sel_hi:[1,0]
	v_pk_mul_f32 v[8:9], v[8:9], v[10:11] op_sel_hi:[1,0]
	v_pk_mul_f32 v[6:7], v[234:235], v[6:7]
	v_pk_mul_f32 v[22:23], v[26:27], v[10:11] op_sel_hi:[1,0]
	v_pk_mul_f32 v[8:9], v[232:233], v[8:9]
	v_pk_mul_f32 v[22:23], v[236:237], v[22:23]
	v_pk_mul_f32 v[24:25], v[28:29], v[10:11] op_sel_hi:[1,0]
	v_pk_mul_f32 v[10:11], v[36:37], v[8:9]
	v_pk_mul_f32 v[18:19], v[230:231], v[24:25]
	v_cvt_pk_bf16_f32 v9, v10, v11
	v_add_co_u32_e32 v10, vcc, 0xd1800000, v4
	v_pk_mul_f32 v[6:7], v[42:43], v[6:7]
	s_nop 0
	v_addc_co_u32_e32 v11, vcc, -1, v5, vcc
	v_pk_mul_f32 v[22:23], v[40:41], v[22:23]
	v_pk_mul_f32 v[18:19], v[38:39], v[18:19]
	v_cmp_lt_i32_e32 vcc, s10, v0
	v_cvt_pk_bf16_f32 v6, v6, v7
	v_cvt_pk_bf16_f32 v7, v22, v23
	v_cvt_pk_bf16_f32 v8, v18, v19
	v_lshl_add_u64 v[4:5], v[4:5], 0, s[14:15]
	s_or_b64 s[18:19], vcc, s[18:19]
	global_store_dwordx4 v[10:11], v[6:9], off
	s_andn2_b64 exec, exec, s[18:19]
	s_cbranch_execnz .LBB0_793
.LBB0_794:
	s_or_b64 exec, exec, s[0:1]
	v_ashrrev_i32_e32 v3, 3, v12
	v_and_b32_e32 v2, 56, v13
	s_movk_i32 s0, 0x90
	v_writelane_b32 v226, s13, 27
	v_mul_lo_u32 v4, v3, s0
	v_lshlrev_b32_e32 v0, 1, v2
	s_movk_i32 s0, 0x50
	s_lshl_b32 s18, s13, 7
	v_add3_u32 v14, s0, v4, v0
	v_mul_u32_u24_e32 v2, 0x90, v2
	v_lshlrev_b32_e32 v4, 1, v3
	v_readlane_b32 s12, v226, 16
	v_add3_u32 v15, s0, v2, v4
	s_ashr_i32 s0, s18, s87
	s_and_b32 s82, s18, s12
	v_lshl_add_u32 v2, s0, 9, v3
	s_lshl_b64 s[0:1], s[82:83], 1
	v_readlane_b32 s10, v228, 54
	s_add_u32 s0, s10, s0
	v_readlane_b32 s11, v228, 55
	s_addc_u32 s1, s11, s1
	v_lshl_add_u64 v[4:5], s[0:1], 0, v[0:1]
	s_or_b32 s0, s18, 64
	s_ashr_i32 s1, s0, s87
	s_and_b32 s82, s0, s12
	v_lshl_add_u32 v6, s1, 9, v3
	s_lshl_b64 s[0:1], s[82:83], 1
	s_add_u32 s0, s10, s0
	s_addc_u32 s1, s11, s1
	v_lshl_add_u64 v[8:9], s[0:1], 0, v[0:1]
	v_add_u32_e32 v10, s48, v3
	v_lshlrev_b32_e32 v0, 4, v12
	v_add_u32_e32 v12, s16, v3
	v_ashrrev_i32_e32 v11, 31, v10
	v_ashrrev_i32_e32 v13, 31, v12
	v_lshlrev_b64 v[10:11], 10, v[10:11]
	v_and_b32_e32 v0, 0x70, v0
	v_lshlrev_b64 v[12:13], 10, v[12:13]
	v_or_b32_e32 v10, v10, v0
	v_or_b32_e32 v12, v12, v0
	v_lshl_add_u64 v[10:11], s[96:97], 0, v[10:11]
	v_lshl_add_u64 v[12:13], s[96:97], 0, v[12:13]
	s_mov_b64 s[0:1], 0
	s_mov_b32 s10, 0x54c1000
	s_barrier
	v_ashrrev_i32_e32 v3, 31, v2
	v_lshlrev_b64 v[16:17], s87, v[2:3]
	v_lshl_add_u64 v[16:17], v[16:17], 1, v[4:5]
	global_load_dwordx4 v[230:233], v[16:17], off
	v_add_u32_e32 v2, 64, v2
.LBB0_795:
	v_ashrrev_i32_e32 v7, 31, v6
	v_lshlrev_b64 v[246:247], s87, v[6:7]
	v_lshl_add_u64 v[246:247], v[246:247], 1, v[8:9]
	global_load_dwordx4 v[234:237], v[246:247], off
	v_add_u32_e32 v6, 64, v6
	v_lshl_add_u64 v[20:21], v[12:13], 0, s[0:1]
	v_add_co_u32_e32 v20, vcc, s10, v20
	s_nop 1
	v_addc_co_u32_e32 v21, vcc, 0, v21, vcc
	s_waitcnt vmcnt(1)
	ds_write_b128 v14, v[230:233]
	s_waitcnt lgkmcnt(0)
	s_barrier
	ds_read_u16 v238, v15
	ds_read_u16 v239, v15 offset:144
	ds_read_u16 v240, v15 offset:288
	ds_read_u16 v241, v15 offset:432
	ds_read_u16 v242, v15 offset:576
	ds_read_u16 v243, v15 offset:720
	ds_read_u16 v244, v15 offset:864
	ds_read_u16 v245, v15 offset:1008
	s_waitcnt lgkmcnt(0)
	v_lshl_or_b32 v16, v239, 16, v238
	v_lshl_or_b32 v17, v241, 16, v240
	v_lshl_or_b32 v18, v243, 16, v242
	v_lshl_or_b32 v19, v245, 16, v244
	global_store_dwordx4 v[20:21], v[16:19], off
	s_barrier
	s_cmpk_eq_i32 s0, 0x380
	s_cbranch_scc1 .Lpm_tnopf
	v_ashrrev_i32_e32 v3, 31, v2
	v_lshlrev_b64 v[246:247], s87, v[2:3]
	v_lshl_add_u64 v[246:247], v[246:247], 1, v[4:5]
	global_load_dwordx4 v[230:233], v[246:247], off
	v_add_u32_e32 v2, 64, v2
.Lpm_tnopf:
	v_lshl_add_u64 v[20:21], v[10:11], 0, s[0:1]
	s_add_u32 s0, s0, 0x80
	s_addc_u32 s1, s1, 0
	v_add_co_u32_e32 v20, vcc, s10, v20
	s_nop 1
	v_addc_co_u32_e32 v21, vcc, 0, v21, vcc
	s_waitcnt vmcnt(1)
	ds_write_b128 v14, v[234:237]
	s_waitcnt lgkmcnt(0)
	s_barrier
	ds_read_u16 v238, v15
	ds_read_u16 v239, v15 offset:144
	ds_read_u16 v240, v15 offset:288
	ds_read_u16 v241, v15 offset:432
	ds_read_u16 v242, v15 offset:576
	ds_read_u16 v243, v15 offset:720
	ds_read_u16 v244, v15 offset:864
	ds_read_u16 v245, v15 offset:1008
	s_waitcnt lgkmcnt(0)
	v_lshl_or_b32 v16, v239, 16, v238
	v_lshl_or_b32 v17, v241, 16, v240
	v_lshl_or_b32 v18, v243, 16, v242
	v_lshl_or_b32 v19, v245, 16, v244
	global_store_dwordx4 v[20:21], v[16:19], off
	s_barrier
	s_cmpk_lg_i32 s0, 0x400
	s_cbranch_scc1 .LBB0_795
	v_mov_b32_e32 v0, v186
	s_ashr_i32 s17, s16, 31
	v_ashrrev_i32_e32 v2, 31, v0
	v_lshrrev_b32_e32 v2, 30, v2
	v_add_u32_e32 v3, v0, v2
	v_ashrrev_i32_e32 v2, 2, v3
	v_and_b32_e32 v3, -4, v3
	v_sub_u32_e32 v0, v0, v3
	v_ashrrev_i32_e32 v3, 31, v2
	s_lshl_b64 s[0:1], s[16:17], 12
	v_lshlrev_b64 v[4:5], 12, v[2:3]
	v_lshlrev_b32_e32 v6, 8, v0
	v_ashrrev_i32_e32 v7, 31, v6
	v_lshl_add_u64 v[4:5], v[4:5], 0, s[0:1]
	v_readlane_b32 s0, v226, 19
	v_lshl_add_u64 v[4:5], v[6:7], 2, v[4:5]
	v_readlane_b32 s1, v226, 20
	v_mov_b32_e32 v3, 0
	s_nop 0
	v_lshl_add_u64 v[4:5], s[0:1], 0, v[4:5]
	s_mov_b64 s[0:1], 0
	v_mov_b32_e32 v246, v4
	v_mov_b32_e32 v247, v5
	s_mov_b32 s0, 0
	global_load_dwordx4 v[6:9], v[246:247], off
	global_load_dwordx4 v[10:13], v[246:247], off offset:16
	global_load_dwordx4 v[14:17], v[246:247], off offset:32
	global_load_dwordx4 v[18:21], v[246:247], off offset:48
	v_lshl_add_u64 v[246:247], v[246:247], 0, 64
